# P0 row loop: norm gains fetched once before the loop instead of one load + full vmcnt drain behind every store
# baseline (speedup 1.0000x reference)
.LBB0_27:
	s_cmp_gt_i32 s59, 0x81ff
	v_mov_b32_e32 v0, v252
	v_mbcnt_lo_u32_b32 v253, -1, 0
	s_cbranch_scc1 .LBB0_36
	v_lshlrev_b32_e32 v0, 2, v0
	v_and_b32_e32 v0, 0xfc, v0
	v_mov_b32_e32 v3, 0
	v_lshlrev_b32_e32 v2, 2, v0
	s_waitcnt lgkmcnt(0)
	s_cmp_eq_u64 s[6:7], 0
	v_lshl_add_u64 v[32:33], s[6:7], 0, v[2:3]
	v_lshlrev_b32_e32 v2, 1, v0
	s_cselect_b64 s[12:13], -1, 0
	s_cmp_lg_u64 s[6:7], 0
	v_lshl_add_u64 v[2:3], s[14:15], 0, v[2:3]
	s_mov_b64 s[6:7], 0x2f00000
	v_lshl_add_u64 v[34:35], v[2:3], 0, s[6:7]
	s_cselect_b64 s[6:7], -1, 0
	v_lshlrev_b32_e32 v37, 2, v0
	v_cndmask_b32_e64 v0, 0, 1, s[6:7]
	v_cmp_ne_u32_e64 s[6:7], 1, v0
	v_mov_b32_e32 v38, 0x358637bd
	v_mbcnt_hi_u32_b32 v39, -1, v253
	s_mov_b32 s28, s59
	global_load_dwordx4 v[64:67], v[32:33], off
	global_load_dwordx4 v[68:71], v[32:33], off offset:1024
	global_load_dwordx4 v[72:75], v[32:33], off offset:2048
	global_load_dwordx4 v[76:79], v[32:33], off offset:3072
	s_waitcnt vmcnt(0)
	s_branch .LBB0_30

.LBB0_34:
	v_mov_b32_e32 v40, v64
	v_mov_b32_e32 v41, v65
	v_mov_b32_e32 v42, v66
	v_mov_b32_e32 v43, v67
	s_waitcnt vmcnt(3)
	v_pk_mul_f32 v[44:45], v[30:31], v[30:31]
	v_pk_mul_f32 v[46:47], v[28:29], v[28:29]
	s_waitcnt vmcnt(2)
	v_pk_mul_f32 v[48:49], v[26:27], v[26:27]
	v_pk_mul_f32 v[50:51], v[24:25], v[24:25]
	v_pk_mov_b32 v[56:57], v[46:47], v[44:45] op_sel:[1,0]
	v_mov_b32_e32 v47, v45
	v_pk_mov_b32 v[44:45], v[50:51], v[48:49] op_sel:[1,0]
	v_mov_b32_e32 v51, v49
	s_waitcnt vmcnt(0)
	v_mul_f32_e32 v55, v16, v16
	v_mul_f32_e32 v52, v21, v21
	v_mul_f32_e32 v54, v23, v23
	v_pk_add_f32 v[46:47], v[56:57], v[46:47]
	v_pk_add_f32 v[44:45], v[44:45], v[50:51]
	v_mul_f32_e32 v58, v17, v17
	v_mul_f32_e32 v59, v18, v18
	v_mul_f32_e32 v60, v19, v19
	v_and_b32_e32 v61, 64, v39
	v_pk_fma_f32 v[48:49], v[20:21], v[20:21], v[52:53] op_sel_hi:[1,1,0]
	v_pk_fma_f32 v[52:53], v[22:23], v[22:23], v[54:55] op_sel_hi:[1,1,0]
	v_pk_add_f32 v[46:47], v[46:47], v[46:47] op_sel:[0,1] op_sel_hi:[1,0]
	v_pk_add_f32 v[44:45], v[44:45], v[44:45] op_sel:[0,1] op_sel_hi:[1,0]
	v_xor_b32_e32 v62, 1, v39
	v_add_u32_e32 v54, 64, v61
	v_mov_b32_e32 v49, v59
	v_mov_b32_e32 v53, v60
	v_mov_b32_e32 v47, v55
	v_mov_b32_e32 v45, v58
	v_cmp_lt_i32_e32 vcc, v62, v54
	v_pk_add_f32 v[48:49], v[48:49], v[52:53]
	v_pk_add_f32 v[44:45], v[46:47], v[44:45]
	v_cndmask_b32_e32 v50, v39, v62, vcc
	v_pk_add_f32 v[44:45], v[44:45], v[48:49]
	v_lshlrev_b32_e32 v50, 2, v50
	v_add_f32_e32 v44, v44, v45
	ds_bpermute_b32 v45, v50, v44
	v_xor_b32_e32 v46, 2, v39
	v_cmp_lt_i32_e32 vcc, v46, v54
	s_lshl_b64 s[28:29], s[28:29], 11
	s_waitcnt lgkmcnt(0)
	v_add_f32_e32 v44, v44, v45
	v_cndmask_b32_e32 v46, v39, v46, vcc
	v_lshlrev_b32_e32 v46, 2, v46
	ds_bpermute_b32 v45, v46, v44
	v_xor_b32_e32 v46, 4, v39
	v_cmp_lt_i32_e32 vcc, v46, v54
	s_waitcnt lgkmcnt(0)
	v_add_f32_e32 v44, v44, v45
	v_cndmask_b32_e32 v46, v39, v46, vcc
	v_lshlrev_b32_e32 v46, 2, v46
	ds_bpermute_b32 v45, v46, v44
	v_xor_b32_e32 v46, 8, v39
	v_cmp_lt_i32_e32 vcc, v46, v54
	s_waitcnt lgkmcnt(0)
	v_add_f32_e32 v44, v44, v45
	v_cndmask_b32_e32 v46, v39, v46, vcc
	v_lshlrev_b32_e32 v46, 2, v46
	ds_bpermute_b32 v45, v46, v44
	v_xor_b32_e32 v46, 16, v39
	v_cmp_lt_i32_e32 vcc, v46, v54
	s_waitcnt lgkmcnt(0)
	v_add_f32_e32 v44, v44, v45
	v_cndmask_b32_e32 v46, v39, v46, vcc
	v_lshlrev_b32_e32 v46, 2, v46
	ds_bpermute_b32 v45, v46, v44
	v_xor_b32_e32 v46, 32, v39
	v_cmp_lt_i32_e32 vcc, v46, v54
	s_waitcnt lgkmcnt(0)
	v_add_f32_e32 v44, v44, v45
	v_cndmask_b32_e32 v46, v39, v46, vcc
	v_lshlrev_b32_e32 v46, 2, v46
	ds_bpermute_b32 v45, v46, v44
	v_lshl_add_u64 v[46:47], v[34:35], 0, s[28:29]
	s_waitcnt lgkmcnt(0)
	v_add_f32_e32 v44, v44, v45
	v_fmamk_f32 v44, v44, 0x3a800000, v38
	v_rsq_f32_e32 v44, v44
	s_waitcnt vmcnt(0)
	v_pk_mul_f32 v[30:31], v[30:31], v[42:43]
	v_pk_mul_f32 v[28:29], v[28:29], v[40:41]
	v_pk_mul_f32 v[30:31], v[30:31], v[44:45] op_sel_hi:[1,0]
	v_pk_mul_f32 v[28:29], v[28:29], v[44:45] op_sel_hi:[1,0]
	s_nop 0
	v_cvt_pk_bf16_f32 v28, v28, v29
	v_cvt_pk_bf16_f32 v29, v30, v31
	global_store_dwordx2 v[46:47], v[28:29], off
	v_mov_b32_e32 v28, v68
	v_mov_b32_e32 v29, v69
	v_mov_b32_e32 v30, v70
	v_mov_b32_e32 v31, v71
	v_pk_mul_f32 v[26:27], v[26:27], v[30:31]
	v_pk_mul_f32 v[24:25], v[24:25], v[28:29]
	v_pk_mul_f32 v[26:27], v[26:27], v[44:45] op_sel_hi:[1,0]
	v_pk_mul_f32 v[24:25], v[24:25], v[44:45] op_sel_hi:[1,0]
	s_nop 0
	v_cvt_pk_bf16_f32 v24, v24, v25
	v_cvt_pk_bf16_f32 v25, v26, v27
	global_store_dwordx2 v[46:47], v[24:25], off offset:512
	v_mov_b32_e32 v24, v72
	v_mov_b32_e32 v25, v73
	v_mov_b32_e32 v26, v74
	v_mov_b32_e32 v27, v75
	v_pk_mul_f32 v[22:23], v[22:23], v[26:27]
	v_pk_mul_f32 v[20:21], v[20:21], v[24:25]
	v_pk_mul_f32 v[22:23], v[22:23], v[44:45] op_sel_hi:[1,0]
	v_pk_mul_f32 v[20:21], v[20:21], v[44:45] op_sel_hi:[1,0]
	s_nop 0
	v_cvt_pk_bf16_f32 v20, v20, v21
	v_cvt_pk_bf16_f32 v21, v22, v23
	global_store_dwordx2 v[46:47], v[20:21], off offset:1024
	v_mov_b32_e32 v20, v76
	v_mov_b32_e32 v21, v77
	v_mov_b32_e32 v22, v78
	v_mov_b32_e32 v23, v79
	v_pk_mul_f32 v[18:19], v[18:19], v[22:23]
	v_pk_mul_f32 v[16:17], v[16:17], v[20:21]
	v_pk_mul_f32 v[18:19], v[44:45], v[18:19] op_sel_hi:[0,1]
	v_pk_mul_f32 v[16:17], v[44:45], v[16:17] op_sel_hi:[0,1]
	v_cvt_pk_bf16_f32 v16, v16, v17
	v_cvt_pk_bf16_f32 v17, v18, v19
	global_store_dwordx2 v[46:47], v[16:17], off offset:1536
	s_or_b64 s[26:27], s[26:27], s[12:13]
	s_and_b64 vcc, exec, s[26:27]
	s_cbranch_vccnz .LBB0_29
.LBB0_35:
	v_mov_b32_e32 v16, v64
	v_mov_b32_e32 v17, v65
	v_mov_b32_e32 v18, v66
	v_mov_b32_e32 v19, v67
	s_waitcnt vmcnt(4)
	v_pk_mul_f32 v[20:21], v[14:15], v[14:15]
	v_pk_mul_f32 v[22:23], v[12:13], v[12:13]
	v_pk_mul_f32 v[24:25], v[10:11], v[10:11]
	v_pk_mul_f32 v[26:27], v[8:9], v[8:9]
	v_pk_mov_b32 v[40:41], v[22:23], v[20:21] op_sel:[1,0]
	v_mov_b32_e32 v23, v21
	v_pk_mov_b32 v[20:21], v[26:27], v[24:25] op_sel:[1,0]
	v_mov_b32_e32 v27, v25
	v_mul_f32_e32 v28, v4, v4
	v_mul_f32_e32 v30, v6, v6
	v_and_b32_e32 v31, 64, v39
	v_pk_add_f32 v[22:23], v[40:41], v[22:23]
	v_pk_add_f32 v[20:21], v[20:21], v[26:27]
	v_pk_fma_f32 v[24:25], v[4:5], v[4:5], v[28:29] op_sel_hi:[1,1,0]
	v_pk_fma_f32 v[28:29], v[6:7], v[6:7], v[30:31] op_sel_hi:[1,1,0]
	v_pk_add_f32 v[22:23], v[22:23], v[22:23] op_sel_hi:[0,1]
	v_pk_add_f32 v[20:21], v[20:21], v[20:21] op_sel_hi:[0,1]
	v_xor_b32_e32 v42, 1, v39
	v_add_u32_e32 v30, 64, v31
	v_mul_f32_e32 v24, v0, v0
	v_mul_f32_e32 v28, v1, v1
	v_mul_f32_e32 v20, v2, v2
	v_mul_f32_e32 v22, v3, v3
	v_cmp_lt_i32_e32 vcc, v42, v30
	v_pk_add_f32 v[24:25], v[24:25], v[28:29]
	v_pk_add_f32 v[20:21], v[20:21], v[22:23]
	v_cndmask_b32_e32 v26, v39, v42, vcc
	v_pk_add_f32 v[20:21], v[24:25], v[20:21]
	v_lshlrev_b32_e32 v26, 2, v26
	v_add_f32_e32 v20, v20, v21
	ds_bpermute_b32 v21, v26, v20
	v_xor_b32_e32 v22, 2, v39
	v_cmp_lt_i32_e32 vcc, v22, v30
	s_ashr_i32 s25, s24, 31
	s_lshl_b64 s[26:27], s[24:25], 11
	v_cndmask_b32_e32 v22, v39, v22, vcc
	v_lshlrev_b32_e32 v22, 2, v22
	s_waitcnt lgkmcnt(0)
	v_add_f32_e32 v20, v20, v21
	ds_bpermute_b32 v21, v22, v20
	v_xor_b32_e32 v22, 4, v39
	v_cmp_lt_i32_e32 vcc, v22, v30
	s_waitcnt lgkmcnt(0)
	v_add_f32_e32 v20, v20, v21
	v_cndmask_b32_e32 v22, v39, v22, vcc
	v_lshlrev_b32_e32 v22, 2, v22
	ds_bpermute_b32 v21, v22, v20
	v_xor_b32_e32 v22, 8, v39
	v_cmp_lt_i32_e32 vcc, v22, v30
	s_waitcnt lgkmcnt(0)
	v_add_f32_e32 v20, v20, v21
	v_cndmask_b32_e32 v22, v39, v22, vcc
	v_lshlrev_b32_e32 v22, 2, v22
	ds_bpermute_b32 v21, v22, v20
	v_xor_b32_e32 v22, 16, v39
	v_cmp_lt_i32_e32 vcc, v22, v30
	s_waitcnt lgkmcnt(0)
	v_add_f32_e32 v20, v20, v21
	v_cndmask_b32_e32 v22, v39, v22, vcc
	v_lshlrev_b32_e32 v22, 2, v22
	ds_bpermute_b32 v21, v22, v20
	v_xor_b32_e32 v22, 32, v39
	v_cmp_lt_i32_e32 vcc, v22, v30
	s_waitcnt lgkmcnt(0)
	v_add_f32_e32 v20, v20, v21
	v_cndmask_b32_e32 v22, v39, v22, vcc
	v_lshlrev_b32_e32 v22, 2, v22
	ds_bpermute_b32 v21, v22, v20
	v_lshl_add_u64 v[22:23], v[34:35], 0, s[26:27]
	s_waitcnt lgkmcnt(0)
	v_add_f32_e32 v20, v20, v21
	v_fmamk_f32 v20, v20, 0x3a800000, v38
	v_rsq_f32_e32 v20, v20
	v_pk_mul_f32 v[18:19], v[14:15], v[18:19]
	v_pk_mul_f32 v[16:17], v[12:13], v[16:17]
	v_pk_mul_f32 v[18:19], v[18:19], v[20:21] op_sel_hi:[1,0]
	v_pk_mul_f32 v[16:17], v[16:17], v[20:21] op_sel_hi:[1,0]
	s_nop 0
	v_cvt_pk_bf16_f32 v16, v16, v17
	v_cvt_pk_bf16_f32 v17, v18, v19
	global_store_dwordx2 v[22:23], v[16:17], off
	v_mov_b32_e32 v16, v68
	v_mov_b32_e32 v17, v69
	v_mov_b32_e32 v18, v70
	v_mov_b32_e32 v19, v71
	v_pk_mul_f32 v[18:19], v[10:11], v[18:19]
	v_pk_mul_f32 v[16:17], v[8:9], v[16:17]
	v_pk_mul_f32 v[18:19], v[18:19], v[20:21] op_sel_hi:[1,0]
	v_pk_mul_f32 v[16:17], v[16:17], v[20:21] op_sel_hi:[1,0]
	s_nop 0
	v_cvt_pk_bf16_f32 v16, v16, v17
	v_cvt_pk_bf16_f32 v17, v18, v19
	global_store_dwordx2 v[22:23], v[16:17], off offset:512
	v_mov_b32_e32 v16, v72
	v_mov_b32_e32 v17, v73
	v_mov_b32_e32 v18, v74
	v_mov_b32_e32 v19, v75
	v_pk_mul_f32 v[18:19], v[6:7], v[18:19]
	v_pk_mul_f32 v[16:17], v[4:5], v[16:17]
	v_pk_mul_f32 v[18:19], v[18:19], v[20:21] op_sel_hi:[1,0]
	v_pk_mul_f32 v[16:17], v[16:17], v[20:21] op_sel_hi:[1,0]
	s_nop 0
	v_cvt_pk_bf16_f32 v16, v16, v17
	v_cvt_pk_bf16_f32 v17, v18, v19
	global_store_dwordx2 v[22:23], v[16:17], off offset:1024
	v_mov_b32_e32 v16, v76
	v_mov_b32_e32 v17, v77
	v_mov_b32_e32 v18, v78
	v_mov_b32_e32 v19, v79
	v_pk_mul_f32 v[18:19], v[2:3], v[18:19]
	v_pk_mul_f32 v[16:17], v[0:1], v[16:17]
	v_pk_mul_f32 v[18:19], v[20:21], v[18:19] op_sel_hi:[0,1]
	v_pk_mul_f32 v[16:17], v[20:21], v[16:17] op_sel_hi:[0,1]
	v_cvt_pk_bf16_f32 v16, v16, v17
	v_cvt_pk_bf16_f32 v17, v18, v19
	global_store_dwordx2 v[22:23], v[16:17], off offset:1536
	s_branch .LBB0_29
